# phase 0 f32 to bf16 conversion loops: two iterations per trip with four loads in flight on the 256-workgroup grid (general loop kept as fallback)
# speedup vs baseline: 1.0061x; 1.0023x over previous
; DI unsigned pk2(float lo, float hi) { f32x2 v = {lo, hi}; bf2_t b = __builtin_convertvector(v, bf2_t); return __builtin_bit_cast(unsigned, b); }
; DI void conv_vec(const float* src, bf16_t* dst, size_t n8, const int tid) {
;     for (size_t i = (size_t)blockIdx.x * 512 + tid; i < n8; i += (size_t)gridDim.x * 512) {
;         const f32x4 a = *(const f32x4*)(src + i * 8), b = *(const f32x4*)(src + i * 8 + 4);
;         u32x4 w; w.x = pk2(a[0], a[1]); w.y = pk2(a[2], a[3]); w.z = pk2(b[0], b[1]); w.w = pk2(b[2], b[3]);
;         *(u32x4*)(dst + i * 8) = w;
;     }
; DI void phase_convert(const Args& a, unsigned char* shm, const int tid) {
;     ...
;     conv_vec(a.in[0], (bf16_t*)(a.ws + WS_XB), (size_t)MTOK * 1024 / 8, tid);
.LBB0_703:
	v_readlane_b32 s0, v251, 45
	v_ashrrev_i32_e32 v211, 31, v210
	v_readlane_b32 s1, v251, 46
	v_lshlrev_b64 v[4:5], 5, v[210:211]
	s_nop 0
	v_lshl_add_u64 v[2:3], s[0:1], 0, v[210:211]
	s_mov_b64 s[0:1], 0x800000
	v_cmp_gt_u64_e32 vcc, s[0:1], v[2:3]
	s_and_saveexec_b64 s[0:1], vcc
	s_cbranch_execz .LBB0_706
	s_load_dword s2, s[56:57], 0x10
	v_readlane_b32 s4, v254, 3
	v_readlane_b32 s5, v254, 4
	s_mov_b64 s[22:23], 0
	v_mov_b64_e32 v[10:11], v[2:3]
	v_lshl_add_u64 v[6:7], s[4:5], 0, v[4:5]
	v_readlane_b32 s4, v254, 5
	s_waitcnt lgkmcnt(0)
	s_lshr_b32 s2, s2, 16
	v_readlane_b32 s5, v254, 6
	s_cmp_lg_u32 s2, 0
	s_nop 0
	v_lshl_add_u64 v[8:9], v[210:211], 4, s[4:5]
	s_cselect_b64 s[4:5], -1, 0
	s_cmp_lg_u64 s[4:5], 0
	s_addc_u32 s2, s80, 0
	s_lshl_b64 s[4:5], s[2:3], 9
	s_lshl_b64 s[6:7], s[2:3], 14
	s_lshl_b64 s[8:9], s[2:3], 13
	s_cmpk_lg_i32 s80, 0x100
	s_cbranch_scc1 .LBB0_705
	s_movk_i32 s38, 32
.Lcv_fast1:
	global_load_dwordx4 v[12:15], v[6:7], off offset:-16
	global_load_dwordx4 v[16:19], v[6:7], off
	v_lshl_add_u64 v[20:21], v[6:7], 0, s[6:7]
	global_load_dwordx4 v[22:25], v[20:21], off offset:-16
	global_load_dwordx4 v[26:29], v[20:21], off
	v_lshl_add_u64 v[6:7], v[20:21], 0, s[6:7]
	s_waitcnt vmcnt(2)
	v_cvt_pk_bf16_f32 v12, v12, v13
	v_cvt_pk_bf16_f32 v13, v14, v15
	v_cvt_pk_bf16_f32 v14, v16, v17
	v_cvt_pk_bf16_f32 v15, v18, v19
	global_store_dwordx4 v[8:9], v[12:15], off
	v_lshl_add_u64 v[30:31], v[8:9], 0, s[8:9]
	s_waitcnt vmcnt(1)
	v_cvt_pk_bf16_f32 v22, v22, v23
	v_cvt_pk_bf16_f32 v23, v24, v25
	v_cvt_pk_bf16_f32 v24, v26, v27
	v_cvt_pk_bf16_f32 v25, v28, v29
	global_store_dwordx4 v[30:31], v[22:25], off
	v_lshl_add_u64 v[8:9], v[30:31], 0, s[8:9]
	s_sub_u32 s38, s38, 1
	s_cmp_lg_u32 s38, 0
	s_cbranch_scc1 .Lcv_fast1
	s_branch .LBB0_706

; DI unsigned pk2(float lo, float hi) { f32x2 v = {lo, hi}; bf2_t b = __builtin_convertvector(v, bf2_t); return __builtin_bit_cast(unsigned, b); }
; DI void conv_vec(const float* src, bf16_t* dst, size_t n8, const int tid) {
;     for (size_t i = (size_t)blockIdx.x * 512 + tid; i < n8; i += (size_t)gridDim.x * 512) {
;         const f32x4 a = *(const f32x4*)(src + i * 8), b = *(const f32x4*)(src + i * 8 + 4);
;         u32x4 w; w.x = pk2(a[0], a[1]); w.y = pk2(a[2], a[3]); w.z = pk2(b[0], b[1]); w.w = pk2(b[2], b[3]);
;         *(u32x4*)(dst + i * 8) = w;
;     }
; DI void phase_convert(const Args& a, unsigned char* shm, const int tid) {
;     ...
;     conv_vec(a.in[1], (bf16_t*)(a.ws + WS_PB), (size_t)2 * MTOK * 256 / 8, tid);
.LBB0_706:
	s_or_b64 exec, exec, s[0:1]
	s_mov_b64 s[0:1], 0x400000
	s_mov_b32 s40, 0x409b43d5
	v_cmp_gt_u64_e32 vcc, s[0:1], v[2:3]
	s_and_saveexec_b64 s[0:1], vcc
	s_cbranch_execz .LBB0_709
	s_load_dword s2, s[56:57], 0x10
	v_readlane_b32 s4, v254, 23
	v_readlane_b32 s5, v254, 24
	s_mov_b64 s[22:23], 0
	s_waitcnt lgkmcnt(0)
	s_lshr_b32 s2, s2, 16
	v_lshl_add_u64 v[4:5], s[4:5], 0, v[4:5]
	v_readlane_b32 s4, v254, 27
	v_readlane_b32 s5, v254, 28
	s_cmp_lg_u32 s2, 0
	s_nop 0
	v_lshl_add_u64 v[6:7], v[210:211], 4, s[4:5]
	s_cselect_b64 s[4:5], -1, 0
	s_cmp_lg_u64 s[4:5], 0
	s_addc_u32 s2, s80, 0
	s_lshl_b64 s[4:5], s[2:3], 9
	s_lshl_b64 s[6:7], s[2:3], 14
	s_lshl_b64 s[8:9], s[2:3], 13
	s_cmpk_lg_i32 s80, 0x100
	s_cbranch_scc1 .LBB0_708
	s_movk_i32 s38, 16
.Lcv_fast2:
	global_load_dwordx4 v[8:11], v[4:5], off offset:-16
	global_load_dwordx4 v[12:15], v[4:5], off
	v_lshl_add_u64 v[20:21], v[4:5], 0, s[6:7]
	global_load_dwordx4 v[22:25], v[20:21], off offset:-16
	global_load_dwordx4 v[26:29], v[20:21], off
	v_lshl_add_u64 v[4:5], v[20:21], 0, s[6:7]
	s_waitcnt vmcnt(2)
	v_cvt_pk_bf16_f32 v8, v8, v9
	v_cvt_pk_bf16_f32 v9, v10, v11
	v_cvt_pk_bf16_f32 v10, v12, v13
	v_cvt_pk_bf16_f32 v11, v14, v15
	global_store_dwordx4 v[6:7], v[8:11], off
	v_lshl_add_u64 v[30:31], v[6:7], 0, s[8:9]
	s_waitcnt vmcnt(1)
	v_cvt_pk_bf16_f32 v22, v22, v23
	v_cvt_pk_bf16_f32 v23, v24, v25
	v_cvt_pk_bf16_f32 v24, v26, v27
	v_cvt_pk_bf16_f32 v25, v28, v29
	global_store_dwordx4 v[30:31], v[22:25], off
	v_lshl_add_u64 v[6:7], v[30:31], 0, s[8:9]
	s_sub_u32 s38, s38, 1
	s_cmp_lg_u32 s38, 0
	s_cbranch_scc1 .Lcv_fast2
	s_branch .LBB0_709
